# FoX loop: C-operand (bias) LDS reads for the first sub-tile issued as soon as its score registers are consumed, so the next tile's score MFMAs do not wait on LDS
# baseline (speedup 1.0000x reference)
.Lfx_body:
	s_add_i32 s37, s49, 0x18000
	s_and_b32 s37, s37, 0xc000
	v_add_u32_e32 v1, s37, v189
	ds_read_b128 v[126:129], v1 offset:32768
	ds_read_b128 v[106:109], v1 offset:40960
	ds_read_b128 v[98:101], v1 offset:33792
	ds_read_b128 v[102:105], v1 offset:41984
	ds_read_b128 v[86:89], v1 offset:34816
	ds_read_b128 v[94:97], v1 offset:43008
	ds_read_b128 v[82:85], v1 offset:35840
	ds_read_b128 v[90:93], v1 offset:44032
	s_add_i32 s37, s49, 0xc000
	s_and_b32 s37, s37, 0xc000
	v_add_u32_e32 v194, s37, v189
	v_add_u32_e32 v195, 0xffffff00, v175
	v_max_i32_e32 v195, v195, v0
	v_mfma_f32_32x32x16_bf16 v[18:33], v[158:161], v[122:125], v[18:33]
	v_exp_f32_e32 v208, v34
	v_exp_f32_e32 v209, v35
	v_exp_f32_e32 v210, v36
	v_exp_f32_e32 v211, v37
	ds_read_b128 v[158:161], v194 offset:36864
	v_mfma_f32_32x32x16_bf16 v[18:33], v[154:157], v[118:121], v[18:33]
	v_exp_f32_e32 v212, v38
	v_exp_f32_e32 v213, v39
	v_exp_f32_e32 v214, v40
	v_exp_f32_e32 v215, v41
	ds_read_b128 v[154:157], v194 offset:37888
	v_mfma_f32_32x32x16_bf16 v[2:17], v[142:145], v[122:125], v[2:17]
	v_exp_f32_e32 v216, v42
	v_exp_f32_e32 v217, v43
	v_exp_f32_e32 v218, v44
	v_exp_f32_e32 v219, v45
	ds_read_b128 v[142:145], v194 offset:38912
	v_mfma_f32_32x32x16_bf16 v[18:33], v[150:153], v[114:117], v[18:33]
	v_exp_f32_e32 v220, v46
	v_exp_f32_e32 v221, v47
	v_exp_f32_e32 v222, v48
	v_exp_f32_e32 v223, v49
	ds_read_b128 v[150:153], v194 offset:45056
	ds_read_b128 v[34:37], v195
	ds_read_b128 v[38:41], v195 offset:16
	ds_read_b128 v[42:45], v195 offset:64
	ds_read_b128 v[46:49], v195 offset:80
	v_mfma_f32_32x32x16_bf16 v[2:17], v[138:141], v[118:121], v[2:17]
	v_exp_f32_e32 v224, v50
	v_exp_f32_e32 v225, v51
	v_exp_f32_e32 v226, v52
	v_exp_f32_e32 v227, v53
	ds_read_b128 v[138:141], v194 offset:39936
	v_mfma_f32_32x32x16_bf16 v[18:33], v[146:149], v[110:113], v[18:33]
	v_exp_f32_e32 v228, v54
	v_exp_f32_e32 v229, v55
	v_exp_f32_e32 v230, v56
	v_exp_f32_e32 v231, v57
	ds_read_b128 v[146:149], v194 offset:46080
	v_mfma_f32_32x32x16_bf16 v[2:17], v[134:137], v[114:117], v[2:17]
	v_exp_f32_e32 v244, v58
	v_exp_f32_e32 v245, v59
	v_exp_f32_e32 v246, v60
	v_exp_f32_e32 v247, v61
	ds_read_b128 v[134:137], v194 offset:47104
	v_mfma_f32_32x32x16_bf16 v[2:17], v[130:133], v[110:113], v[2:17]
	v_exp_f32_e32 v248, v62
	v_exp_f32_e32 v249, v63
	v_exp_f32_e32 v250, v64
	v_exp_f32_e32 v251, v65
	ds_read_b128 v[130:133], v194 offset:48128
	ds_read_b128 v[50:53], v195 offset:128
	ds_read_b128 v[54:57], v195 offset:144
	ds_read_b128 v[58:61], v195 offset:192
	ds_read_b128 v[62:65], v195 offset:208
	v_add_f32_e32 v110, v208, v209
	v_add_f32_e32 v111, v210, v211
	v_add_f32_e32 v112, v212, v213
	v_add_f32_e32 v113, v214, v215
	s_waitcnt lgkmcnt(8)
	v_mfma_f32_32x32x16_bf16 v[34:49], v[126:129], v[66:69], v[34:49]
	v_add_f32_e32 v110, v216, v110
	v_add_f32_e32 v111, v217, v111
	v_add_f32_e32 v112, v218, v112
	s_waitcnt lgkmcnt(0)
	v_mfma_f32_32x32x16_bf16 v[50:65], v[106:109], v[66:69], v[50:65]
	v_add_f32_e32 v113, v219, v113
	v_add_f32_e32 v110, v220, v110
	v_add_f32_e32 v111, v221, v111
	v_mfma_f32_32x32x16_bf16 v[34:49], v[98:101], v[70:73], v[34:49]
	v_add_f32_e32 v112, v222, v112
	v_add_f32_e32 v113, v223, v113
	v_add_f32_e32 v110, v224, v110
	v_mfma_f32_32x32x16_bf16 v[50:65], v[102:105], v[70:73], v[50:65]
	v_add_f32_e32 v111, v225, v111
	v_add_f32_e32 v112, v226, v112
	v_add_f32_e32 v113, v227, v113
	v_mfma_f32_32x32x16_bf16 v[34:49], v[86:89], v[74:77], v[34:49]
	v_add_f32_e32 v110, v228, v110
	v_add_f32_e32 v111, v229, v111
	v_add_f32_e32 v112, v230, v112
	v_mfma_f32_32x32x16_bf16 v[50:65], v[94:97], v[74:77], v[50:65]
	v_add_f32_e32 v113, v231, v113
	v_add_f32_e32 v110, v244, v110
	v_add_f32_e32 v111, v245, v111
	v_mfma_f32_32x32x16_bf16 v[34:49], v[82:85], v[78:81], v[34:49]
	v_add_f32_e32 v112, v246, v112
	v_add_f32_e32 v113, v247, v113
	v_add_f32_e32 v110, v248, v110
	v_mfma_f32_32x32x16_bf16 v[50:65], v[90:93], v[78:81], v[50:65]
	v_add_f32_e32 v111, v249, v111
	v_add_f32_e32 v112, v250, v112
	v_add_f32_e32 v113, v251, v113
	v_mfma_f32_32x32x16_bf16 v[34:49], v[196:199], v[162:165], v[34:49]
	v_mfma_f32_32x32x16_bf16 v[50:65], v[196:199], v[162:165], v[50:65]
	v_add_f32_e32 v110, v110, v111
	v_add_f32_e32 v112, v112, v113
	v_add_f32_e32 v114, v110, v112
	v_cmp_lt_f32_e32 vcc, 0x49800000, v114
	s_cbranch_vccnz .Lfx_rare
